# stack of all attention micro-edits: self-max folding with safe slot deletion + all packed-add splits + early first K/V chunk in the MLA unit prologue
# baseline (speedup 1.0000x reference)
.LBB0_676:
	v_fma_f32 v0, v122, s46, -v168
	v_exp_f32_e32 v122, v0
	v_fma_f32 v0, v123, s46, -v168
	v_exp_f32_e32 v192, v0
	v_fma_f32 v0, v124, s46, -v168
	v_exp_f32_e32 v123, v0
	v_fma_f32 v0, v125, s46, -v168
	v_exp_f32_e32 v193, v0
	v_fma_f32 v0, v126, s46, -v168
	v_exp_f32_e32 v124, v0
	v_fma_f32 v0, v127, s46, -v168
	v_exp_f32_e32 v194, v0
	v_fma_f32 v0, v128, s46, -v168
	v_exp_f32_e32 v125, v0
	v_fma_f32 v0, v129, s46, -v168
	v_exp_f32_e32 v195, v0
	v_add_f32_e32 v126, v122, v192
	v_add_f32_e32 v127, v123, v193
	s_nop 0
	v_add_f32_e32 v0, v126, v127
	v_add_f32_e32 v126, v124, v194
	v_add_f32_e32 v127, v125, v195
	v_add_f32_e32 v169, 0, v0
	v_add_f32_e32 v196, v126, v126
	v_add_f32_e32 v197, v126, v127
	v_fma_f32 v126, v131, s46, -v168
	v_exp_f32_e32 v164, v126
	v_fma_f32 v126, v132, s46, -v168
	v_exp_f32_e32 v177, v126
	v_fma_f32 v126, v133, s46, -v168
	v_exp_f32_e32 v179, v126
	v_fma_f32 v126, v134, s46, -v168
	v_fma_f32 v0, v130, s46, -v168
	v_exp_f32_e32 v130, v126
	v_fma_f32 v126, v135, s46, -v168
	v_exp_f32_e32 v132, v126
	v_fma_f32 v126, v136, s46, -v168
	v_exp_f32_e32 v0, v0
	v_exp_f32_e32 v196, v126
	v_fma_f32 v126, v137, s46, -v168
	v_exp_f32_e32 v168, v126
	v_add_f32_e32 v131, v0, v164
	v_add_f32_e32 v133, v177, v179
	v_add_f32_e32 v126, v130, v132
	v_add_f32_e32 v127, v131, v133
	v_add_f32_e32 v128, v196, v168
	v_add_f32_e32 v129, v197, v169
	s_nop 0
	v_add_f32_e32 v126, v126, v128
	v_add_f32_e32 v127, v127, v129
	s_nop 0
	v_add_f32_e32 v126, v126, v127
	ds_bpermute_b32 v127, v155, v126
	s_waitcnt lgkmcnt(0)
	v_add_f32_e32 v126, v126, v127
	ds_bpermute_b32 v127, v176, v126
	s_waitcnt lgkmcnt(0)
	v_add_f32_e32 v126, v126, v127
	v_add_f32_e32 v160, v160, v126
	v_max_f32_e32 v126, v108, v109
	v_max_f32_e32 v127, v112, v113
	v_max3_f32 v126, v106, v107, v126
	v_max3_f32 v127, v110, v111, v127
	v_max3_f32 v126, v126, s51, v127
	v_max_f32_e32 v127, v116, v117
	v_max_f32_e32 v128, v120, v121
	v_max3_f32 v127, v114, v115, v127
	v_max3_f32 v128, v118, v119, v128
	v_max3_f32 v131, v126, v127, v128
	ds_bpermute_b32 v133, v155, v131
	v_cvt_pk_bf16_f32 v126, v122, v192
	v_cvt_pk_bf16_f32 v127, v123, v193
	v_cvt_pk_bf16_f32 v128, v124, v194
	v_cvt_pk_bf16_f32 v129, v125, v195
	s_waitcnt lgkmcnt(0)
	v_max_f32_e32 v131, v131, v133
	ds_bpermute_b32 v133, v176, v131
	v_cvt_pk_bf16_f32 v122, v0, v164
	v_cvt_pk_bf16_f32 v123, v177, v179
	v_cvt_pk_bf16_f32 v124, v130, v132
	v_add_f32_e32 v130, 0x41000000, v165
	s_waitcnt lgkmcnt(0)
	v_max_f32_e32 v0, v131, v133
	v_mul_f32_e32 v0, 0x3e16c740, v0
	v_cmp_gt_f32_e32 vcc, v0, v130
	v_cvt_pk_bf16_f32 v125, v196, v168
	s_cbranch_vccz .LBB0_657
	s_nop 0
	v_cndmask_b32_e32 v167, v165, v0, vcc
	v_sub_f32_e32 v0, v165, v167
	v_exp_f32_e32 v0, v0
	v_mov_b32_e32 v165, v167
	v_mul_f32_e32 v161, v161, v0
	v_pk_mul_f32 v[104:105], v[104:105], v[0:1] op_sel_hi:[1,0]
	v_pk_mul_f32 v[102:103], v[102:103], v[0:1] op_sel_hi:[1,0]
	v_pk_mul_f32 v[100:101], v[100:101], v[0:1] op_sel_hi:[1,0]
	v_pk_mul_f32 v[98:99], v[98:99], v[0:1] op_sel_hi:[1,0]
	v_pk_mul_f32 v[96:97], v[96:97], v[0:1] op_sel_hi:[1,0]
	v_pk_mul_f32 v[94:95], v[94:95], v[0:1] op_sel_hi:[1,0]
	v_pk_mul_f32 v[92:93], v[92:93], v[0:1] op_sel_hi:[1,0]
	v_pk_mul_f32 v[90:91], v[90:91], v[0:1] op_sel_hi:[1,0]
	s_branch .LBB0_657
